# residrev_peel_noZeroing
# speedup vs baseline: 1.0110x; 1.0019x over previous
.LBB0_468:
	s_ashr_i32 s37, s36, 31
	s_lshl_b64 s[40:41], s[36:37], 19
	s_add_u32 s40, s82, s40
	s_addc_u32 s41, s83, s41
	s_and_b64 s[42:43], s[10:11], exec
	s_cselect_b32 s5, s41, s9
	s_cselect_b32 s7, s40, s8
	s_ashr_i32 s39, s38, 31
	s_lshl_b64 s[42:43], s[38:39], 19
	s_add_u32 s42, s12, s42
	s_addc_u32 s43, s13, s43
	s_and_b64 s[44:45], s[10:11], exec
	s_cselect_b32 s37, s43, s3
	s_cselect_b32 s39, s42, s2
	s_add_u32 s8, s8, 0x40080
	s_addc_u32 s9, s9, 0
	s_add_u32 s33, s2, 0x100
	s_addc_u32 s61, s3, 0
	s_mov_b32 s62, -2
	s_add_u32 s2, s8, 0xfffc0080
	s_addc_u32 s3, s9, -1
	s_add_i32 s63, 0, 0x10000
	s_cmp_eq_u32 s62, 12
	s_cselect_b32 s45, s5, s3
	s_cselect_b32 s44, s7, s2
	s_cselect_b32 s3, s37, s61
	s_cselect_b32 s2, s39, s33
	s_add_i32 s66, 0, 0x14000
	v_add_u32_e32 v70, s63, v211
	v_add_u32_e32 v142, s66, v211
	ds_read_b128 v[50:53], v70
	ds_read_b128 v[54:57], v70 offset:1024
	ds_read_b128 v[66:69], v70 offset:2048
	ds_read_b128 v[70:73], v70 offset:3072
	ds_read_b128 v[90:93], v142
	ds_read_b128 v[110:113], v142 offset:1024
	ds_read_b128 v[126:129], v142 offset:2048
	ds_read_b128 v[142:145], v142 offset:3072
	v_lshl_add_u64 v[214:215], s[8:9], 0, v[172:173]
	s_add_i32 m0, s50, 0xc000
	ds_read_b128 v[176:179], v213
	ds_read_b128 v[180:183], v213 offset:1024
	ds_read_b128 v[186:189], v213 offset:2048
	ds_read_b128 v[190:193], v213 offset:3072
	ds_read_b128 v[194:197], v213 offset:4096
	ds_read_b128 v[198:201], v213 offset:5120
	ds_read_b128 v[202:205], v213 offset:6144
	ds_read_b128 v[206:209], v213 offset:7168
	global_load_lds_dwordx4 v[214:215], off
	v_lshl_add_u64 v[214:215], s[8:9], 0, v[174:175]
	s_add_i32 m0, s50, 0xe000
	s_nop 0
	global_load_lds_dwordx4 v[214:215], off
	s_waitcnt vmcnt(8)
	s_waitcnt lgkmcnt(0)
	s_barrier
	s_setprio 1
	s_waitcnt lgkmcnt(0)
	v_mfma_f32_16x16x32_bf16 v[158:161], v[50:53], v[176:179], 0
	v_mfma_f32_16x16x32_bf16 v[154:157], v[66:69], v[176:179], 0
	v_mfma_f32_16x16x32_bf16 v[138:141], v[50:53], v[186:189], 0
	v_mfma_f32_16x16x32_bf16 v[134:137], v[66:69], v[186:189], 0
	v_mfma_f32_16x16x32_bf16 v[118:121], v[50:53], v[194:197], 0
	v_mfma_f32_16x16x32_bf16 v[114:117], v[66:69], v[194:197], 0
	v_mfma_f32_16x16x32_bf16 v[98:101], v[50:53], v[202:205], 0
	v_mfma_f32_16x16x32_bf16 v[94:97], v[66:69], v[202:205], 0
	v_mfma_f32_16x16x32_bf16 v[158:161], v[54:57], v[180:183], v[158:161]
	v_mfma_f32_16x16x32_bf16 v[154:157], v[70:73], v[180:183], v[154:157]
	v_mfma_f32_16x16x32_bf16 v[138:141], v[54:57], v[190:193], v[138:141]
	v_mfma_f32_16x16x32_bf16 v[134:137], v[70:73], v[190:193], v[134:137]
	v_mfma_f32_16x16x32_bf16 v[118:121], v[54:57], v[198:201], v[118:121]
	v_mfma_f32_16x16x32_bf16 v[114:117], v[70:73], v[198:201], v[114:117]
	v_mfma_f32_16x16x32_bf16 v[98:101], v[54:57], v[206:209], v[98:101]
	v_mfma_f32_16x16x32_bf16 v[94:97], v[70:73], v[206:209], v[94:97]
	s_setprio 0
	s_setprio 1
	v_mfma_f32_16x16x32_bf16 v[150:153], v[90:93], v[176:179], 0
	v_mfma_f32_16x16x32_bf16 v[146:149], v[126:129], v[176:179], 0
	v_mfma_f32_16x16x32_bf16 v[130:133], v[90:93], v[186:189], 0
	v_mfma_f32_16x16x32_bf16 v[122:125], v[126:129], v[186:189], 0
	v_mfma_f32_16x16x32_bf16 v[106:109], v[90:93], v[194:197], 0
	v_mfma_f32_16x16x32_bf16 v[102:105], v[126:129], v[194:197], 0
	v_mfma_f32_16x16x32_bf16 v[86:89], v[90:93], v[202:205], 0
	v_mfma_f32_16x16x32_bf16 v[82:85], v[126:129], v[202:205], 0
	v_mfma_f32_16x16x32_bf16 v[150:153], v[110:113], v[180:183], v[150:153]
	v_mfma_f32_16x16x32_bf16 v[146:149], v[142:145], v[180:183], v[146:149]
	v_mfma_f32_16x16x32_bf16 v[130:133], v[110:113], v[190:193], v[130:133]
	v_mfma_f32_16x16x32_bf16 v[122:125], v[142:145], v[190:193], v[122:125]
	v_mfma_f32_16x16x32_bf16 v[106:109], v[110:113], v[198:201], v[106:109]
	v_mfma_f32_16x16x32_bf16 v[102:105], v[142:145], v[198:201], v[102:105]
	v_mfma_f32_16x16x32_bf16 v[86:89], v[110:113], v[206:209], v[86:89]
	v_mfma_f32_16x16x32_bf16 v[82:85], v[142:145], v[206:209], v[82:85]
	s_setprio 0
	s_barrier
	s_add_i32 s63, s63, s49
	v_lshl_add_u64 v[214:215], s[2:3], 0, v[0:1]
	s_mov_b32 m0, s63
	ds_read_b128 v[176:179], v213 offset:16384
	ds_read_b128 v[180:183], v213 offset:17408
	ds_read_b128 v[186:189], v213 offset:18432
	ds_read_b128 v[190:193], v213 offset:19456
	ds_read_b128 v[194:197], v213 offset:20480
	ds_read_b128 v[198:201], v213 offset:21504
	ds_read_b128 v[202:205], v213 offset:22528
	ds_read_b128 v[206:209], v213 offset:23552
	global_load_lds_dwordx4 v[214:215], off
	s_add_i32 m0, s63, 0x2000
	s_add_u32 s64, s2, 0x40000
	v_lshl_add_u64 v[216:217], s[2:3], 0, v[166:167]
	s_addc_u32 s65, s3, 0
	s_add_i32 s63, s66, s49
	global_load_lds_dwordx4 v[216:217], off
	v_lshl_add_u64 v[218:219], s[64:65], 0, v[0:1]
	s_mov_b32 m0, s63
	v_lshl_add_u64 v[220:221], s[44:45], 0, v[164:165]
	global_load_lds_dwordx4 v[218:219], off
	v_lshl_add_u64 v[218:219], s[64:65], 0, v[166:167]
	s_add_i32 m0, s63, 0x2000
	s_nop 0
	global_load_lds_dwordx4 v[218:219], off
	v_lshl_add_u64 v[218:219], s[44:45], 0, v[162:163]
	s_mov_b32 m0, s50
	s_nop 0
	global_load_lds_dwordx4 v[218:219], off
	s_mov_b32 m0, s51
	s_nop 0
	global_load_lds_dwordx4 v[220:221], off
	s_waitcnt vmcnt(8)
	s_waitcnt lgkmcnt(0)
	s_barrier
	s_setprio 1
	s_waitcnt lgkmcnt(0)
	v_mfma_f32_16x16x32_bf16 v[78:81], v[50:53], v[176:179], 0
	v_mfma_f32_16x16x32_bf16 v[74:77], v[66:69], v[176:179], 0
	v_mfma_f32_16x16x32_bf16 v[46:49], v[50:53], v[186:189], 0
	v_mfma_f32_16x16x32_bf16 v[42:45], v[66:69], v[186:189], 0
	v_mfma_f32_16x16x32_bf16 v[30:33], v[50:53], v[194:197], 0
	v_mfma_f32_16x16x32_bf16 v[26:29], v[66:69], v[194:197], 0
	v_mfma_f32_16x16x32_bf16 v[14:17], v[50:53], v[202:205], 0
	v_mfma_f32_16x16x32_bf16 v[10:13], v[66:69], v[202:205], 0
	v_mfma_f32_16x16x32_bf16 v[78:81], v[54:57], v[180:183], v[78:81]
	v_mfma_f32_16x16x32_bf16 v[74:77], v[70:73], v[180:183], v[74:77]
	v_mfma_f32_16x16x32_bf16 v[46:49], v[54:57], v[190:193], v[46:49]
	v_mfma_f32_16x16x32_bf16 v[42:45], v[70:73], v[190:193], v[42:45]
	v_mfma_f32_16x16x32_bf16 v[30:33], v[54:57], v[198:201], v[30:33]
	v_mfma_f32_16x16x32_bf16 v[26:29], v[70:73], v[198:201], v[26:29]
	v_mfma_f32_16x16x32_bf16 v[14:17], v[54:57], v[206:209], v[14:17]
	v_mfma_f32_16x16x32_bf16 v[10:13], v[70:73], v[206:209], v[10:13]
	s_setprio 0
	s_setprio 1
	v_mfma_f32_16x16x32_bf16 v[38:41], v[90:93], v[186:189], 0
	v_mfma_f32_16x16x32_bf16 v[34:37], v[126:129], v[186:189], 0
	v_mfma_f32_16x16x32_bf16 v[22:25], v[90:93], v[194:197], 0
	v_mfma_f32_16x16x32_bf16 v[18:21], v[126:129], v[194:197], 0
	v_mfma_f32_16x16x32_bf16 v[6:9], v[90:93], v[202:205], 0
	v_mfma_f32_16x16x32_bf16 v[2:5], v[126:129], v[202:205], 0
	v_mfma_f32_16x16x32_bf16 v[50:53], v[90:93], v[176:179], 0
	v_mfma_f32_16x16x32_bf16 v[54:57], v[126:129], v[176:179], 0
	v_mfma_f32_16x16x32_bf16 v[38:41], v[110:113], v[190:193], v[38:41]
	v_mfma_f32_16x16x32_bf16 v[34:37], v[142:145], v[190:193], v[34:37]
	v_mfma_f32_16x16x32_bf16 v[22:25], v[110:113], v[198:201], v[22:25]
	v_mfma_f32_16x16x32_bf16 v[18:21], v[142:145], v[198:201], v[18:21]
	v_mfma_f32_16x16x32_bf16 v[6:9], v[110:113], v[206:209], v[6:9]
	v_mfma_f32_16x16x32_bf16 v[2:5], v[142:145], v[206:209], v[2:5]
	v_mfma_f32_16x16x32_bf16 v[50:53], v[110:113], v[180:183], v[50:53]
	v_mfma_f32_16x16x32_bf16 v[54:57], v[142:145], v[180:183], v[54:57]
	s_setprio 0
	s_barrier
	s_add_i32 s63, 0, 0x18000
	s_add_i32 s64, 0, 0x1c000
	v_add_u32_e32 v70, s63, v211
	v_add_u32_e32 v142, s64, v211
	ds_read_b128 v[58:61], v70
	ds_read_b128 v[62:65], v70 offset:1024
	ds_read_b128 v[66:69], v70 offset:2048
	ds_read_b128 v[70:73], v70 offset:3072
	ds_read_b128 v[90:93], v142
	ds_read_b128 v[110:113], v142 offset:1024
	ds_read_b128 v[126:129], v142 offset:2048
	ds_read_b128 v[142:145], v142 offset:3072
	s_add_u32 s44, s44, 0x40000
	s_addc_u32 s45, s45, 0
	s_mov_b32 m0, s52
	v_lshl_add_u64 v[222:223], s[44:45], 0, v[162:163]
	ds_read_b128 v[176:179], v213 offset:32768
	ds_read_b128 v[180:183], v213 offset:33792
	ds_read_b128 v[186:189], v213 offset:34816
	ds_read_b128 v[190:193], v213 offset:35840
	ds_read_b128 v[194:197], v213 offset:36864
	ds_read_b128 v[198:201], v213 offset:37888
	ds_read_b128 v[202:205], v213 offset:38912
	ds_read_b128 v[206:209], v213 offset:39936
	global_load_lds_dwordx4 v[222:223], off
	v_lshl_add_u64 v[222:223], s[44:45], 0, v[164:165]
	s_mov_b32 m0, s53
	s_nop 0
	global_load_lds_dwordx4 v[222:223], off
	s_waitcnt vmcnt(8)
	s_waitcnt lgkmcnt(0)
	s_barrier
	s_setprio 1
	s_waitcnt lgkmcnt(0)
	v_mfma_f32_16x16x32_bf16 v[158:161], v[58:61], v[176:179], v[158:161]
	v_mfma_f32_16x16x32_bf16 v[154:157], v[66:69], v[176:179], v[154:157]
	v_mfma_f32_16x16x32_bf16 v[138:141], v[58:61], v[186:189], v[138:141]
	v_mfma_f32_16x16x32_bf16 v[134:137], v[66:69], v[186:189], v[134:137]
	v_mfma_f32_16x16x32_bf16 v[118:121], v[58:61], v[194:197], v[118:121]
	v_mfma_f32_16x16x32_bf16 v[114:117], v[66:69], v[194:197], v[114:117]
	v_mfma_f32_16x16x32_bf16 v[98:101], v[58:61], v[202:205], v[98:101]
	v_mfma_f32_16x16x32_bf16 v[94:97], v[66:69], v[202:205], v[94:97]
	v_mfma_f32_16x16x32_bf16 v[158:161], v[62:65], v[180:183], v[158:161]
	v_mfma_f32_16x16x32_bf16 v[154:157], v[70:73], v[180:183], v[154:157]
	v_mfma_f32_16x16x32_bf16 v[138:141], v[62:65], v[190:193], v[138:141]
	v_mfma_f32_16x16x32_bf16 v[134:137], v[70:73], v[190:193], v[134:137]
	v_mfma_f32_16x16x32_bf16 v[118:121], v[62:65], v[198:201], v[118:121]
	v_mfma_f32_16x16x32_bf16 v[114:117], v[70:73], v[198:201], v[114:117]
	v_mfma_f32_16x16x32_bf16 v[98:101], v[62:65], v[206:209], v[98:101]
	v_mfma_f32_16x16x32_bf16 v[94:97], v[70:73], v[206:209], v[94:97]
	s_setprio 0
	s_setprio 1
	v_mfma_f32_16x16x32_bf16 v[150:153], v[90:93], v[176:179], v[150:153]
	v_mfma_f32_16x16x32_bf16 v[146:149], v[126:129], v[176:179], v[146:149]
	v_mfma_f32_16x16x32_bf16 v[130:133], v[90:93], v[186:189], v[130:133]
	v_mfma_f32_16x16x32_bf16 v[122:125], v[126:129], v[186:189], v[122:125]
	v_mfma_f32_16x16x32_bf16 v[106:109], v[90:93], v[194:197], v[106:109]
	v_mfma_f32_16x16x32_bf16 v[102:105], v[126:129], v[194:197], v[102:105]
	v_mfma_f32_16x16x32_bf16 v[86:89], v[90:93], v[202:205], v[86:89]
	v_mfma_f32_16x16x32_bf16 v[82:85], v[126:129], v[202:205], v[82:85]
	v_mfma_f32_16x16x32_bf16 v[150:153], v[110:113], v[180:183], v[150:153]
	v_mfma_f32_16x16x32_bf16 v[146:149], v[142:145], v[180:183], v[146:149]
	v_mfma_f32_16x16x32_bf16 v[130:133], v[110:113], v[190:193], v[130:133]
	v_mfma_f32_16x16x32_bf16 v[122:125], v[142:145], v[190:193], v[122:125]
	v_mfma_f32_16x16x32_bf16 v[106:109], v[110:113], v[198:201], v[106:109]
	v_mfma_f32_16x16x32_bf16 v[102:105], v[142:145], v[198:201], v[102:105]
	v_mfma_f32_16x16x32_bf16 v[86:89], v[110:113], v[206:209], v[86:89]
	v_mfma_f32_16x16x32_bf16 v[82:85], v[142:145], v[206:209], v[82:85]
	s_setprio 0
	s_barrier
	s_add_i32 s44, s63, s49
	v_lshl_add_u64 v[214:215], v[214:215], 0, s[74:75]
	s_mov_b32 m0, s44
	ds_read_b128 v[176:179], v213 offset:49152
	ds_read_b128 v[180:183], v213 offset:50176
	ds_read_b128 v[186:189], v213 offset:51200
	ds_read_b128 v[190:193], v213 offset:52224
	ds_read_b128 v[194:197], v213 offset:53248
	ds_read_b128 v[198:201], v213 offset:54272
	ds_read_b128 v[202:205], v213 offset:55296
	ds_read_b128 v[206:209], v213 offset:56320
	global_load_lds_dwordx4 v[214:215], off
	s_add_i32 m0, s44, 0x2000
	s_add_u32 s2, s2, 0x40080
	v_lshl_add_u64 v[214:215], v[216:217], 0, s[74:75]
	s_addc_u32 s3, s3, 0
	s_add_i32 s44, s64, s49
	global_load_lds_dwordx4 v[214:215], off
	v_lshl_add_u64 v[214:215], s[2:3], 0, v[0:1]
	s_mov_b32 m0, s44
	s_nop 0
	global_load_lds_dwordx4 v[214:215], off
	v_lshl_add_u64 v[214:215], s[2:3], 0, v[166:167]
	s_add_i32 m0, s44, 0x2000
	s_nop 0
	global_load_lds_dwordx4 v[214:215], off
	v_lshl_add_u64 v[214:215], v[218:219], 0, s[74:75]
	s_mov_b32 m0, s55
	s_nop 0
	global_load_lds_dwordx4 v[214:215], off
	v_lshl_add_u64 v[214:215], v[220:221], 0, s[74:75]
	s_mov_b32 m0, s56
	s_nop 0
	global_load_lds_dwordx4 v[214:215], off
	s_waitcnt vmcnt(8)
	s_waitcnt lgkmcnt(0)
	s_barrier
	s_setprio 1
	s_waitcnt lgkmcnt(0)
	v_mfma_f32_16x16x32_bf16 v[78:81], v[58:61], v[176:179], v[78:81]
	v_mfma_f32_16x16x32_bf16 v[74:77], v[66:69], v[176:179], v[74:77]
	v_mfma_f32_16x16x32_bf16 v[46:49], v[58:61], v[186:189], v[46:49]
	v_mfma_f32_16x16x32_bf16 v[42:45], v[66:69], v[186:189], v[42:45]
	v_mfma_f32_16x16x32_bf16 v[30:33], v[58:61], v[194:197], v[30:33]
	v_mfma_f32_16x16x32_bf16 v[26:29], v[66:69], v[194:197], v[26:29]
	v_mfma_f32_16x16x32_bf16 v[14:17], v[58:61], v[202:205], v[14:17]
	v_mfma_f32_16x16x32_bf16 v[10:13], v[66:69], v[202:205], v[10:13]
	v_mfma_f32_16x16x32_bf16 v[78:81], v[62:65], v[180:183], v[78:81]
	v_mfma_f32_16x16x32_bf16 v[74:77], v[70:73], v[180:183], v[74:77]
	v_mfma_f32_16x16x32_bf16 v[46:49], v[62:65], v[190:193], v[46:49]
	v_mfma_f32_16x16x32_bf16 v[42:45], v[70:73], v[190:193], v[42:45]
	v_mfma_f32_16x16x32_bf16 v[30:33], v[62:65], v[198:201], v[30:33]
	v_mfma_f32_16x16x32_bf16 v[26:29], v[70:73], v[198:201], v[26:29]
	v_mfma_f32_16x16x32_bf16 v[14:17], v[62:65], v[206:209], v[14:17]
	v_mfma_f32_16x16x32_bf16 v[10:13], v[70:73], v[206:209], v[10:13]
	s_setprio 0
	s_setprio 1
	v_mfma_f32_16x16x32_bf16 v[50:53], v[90:93], v[176:179], v[50:53]
	v_mfma_f32_16x16x32_bf16 v[62:65], v[110:113], v[180:183], v[50:53]
	v_mfma_f32_16x16x32_bf16 v[50:53], v[126:129], v[176:179], v[54:57]
	v_mfma_f32_16x16x32_bf16 v[38:41], v[90:93], v[186:189], v[38:41]
	v_mfma_f32_16x16x32_bf16 v[34:37], v[126:129], v[186:189], v[34:37]
	v_mfma_f32_16x16x32_bf16 v[22:25], v[90:93], v[194:197], v[22:25]
	v_mfma_f32_16x16x32_bf16 v[18:21], v[126:129], v[194:197], v[18:21]
	v_mfma_f32_16x16x32_bf16 v[6:9], v[90:93], v[202:205], v[6:9]
	v_mfma_f32_16x16x32_bf16 v[2:5], v[126:129], v[202:205], v[2:5]
	v_mfma_f32_16x16x32_bf16 v[58:61], v[142:145], v[180:183], v[50:53]
	v_mfma_f32_16x16x32_bf16 v[38:41], v[110:113], v[190:193], v[38:41]
	v_mfma_f32_16x16x32_bf16 v[34:37], v[142:145], v[190:193], v[34:37]
	v_mfma_f32_16x16x32_bf16 v[22:25], v[110:113], v[198:201], v[22:25]
	v_mfma_f32_16x16x32_bf16 v[18:21], v[142:145], v[198:201], v[18:21]
	v_mfma_f32_16x16x32_bf16 v[6:9], v[110:113], v[206:209], v[6:9]
	v_mfma_f32_16x16x32_bf16 v[2:5], v[142:145], v[206:209], v[2:5]
	s_setprio 0
	s_barrier
	s_add_i32 s62, s62, 2
	s_add_u32 s8, s8, 0x100
	s_addc_u32 s9, s9, 0
	s_add_u32 s33, s33, 0x100
	s_addc_u32 s61, s61, 0
	s_cmp_gt_u32 s62, 13

.LBB0_556:
	s_add_u32 s4, s26, 0x80
	s_addc_u32 s5, s27, 0
	s_add_u32 s26, s2, 0x100
	s_addc_u32 s27, s3, 0
	s_mov_b32 s2, 0
	s_add_i32 s33, s2, 2
	s_add_u32 s45, s4, 0x80
	s_addc_u32 s3, s5, 0
	s_add_i32 s48, 0, 0x10000
	s_cmp_eq_u32 s40, s2
	s_cselect_b32 s3, s23, s3
	s_cselect_b32 s2, s22, s45
	s_cselect_b32 s47, s25, s27
	s_cselect_b32 s46, s24, s26
	s_add_i32 s45, 0, 0x14000
	v_add_u32_e32 v70, s48, v199
	v_add_u32_e32 v158, s45, v199
	ds_read_b128 v[58:61], v70
	ds_read_b128 v[62:65], v70 offset:1024
	ds_read_b128 v[66:69], v70 offset:2048
	ds_read_b128 v[70:73], v70 offset:3072
	ds_read_b128 v[138:141], v158
	ds_read_b128 v[150:153], v158 offset:1024
	ds_read_b128 v[154:157], v158 offset:2048
	ds_read_b128 v[158:161], v158 offset:3072
	v_lshl_add_u64 v[196:197], s[4:5], 0, v[176:177]
	s_add_i32 m0, s30, 0xc000
	ds_read_b128 v[162:165], v201
	ds_read_b128 v[166:169], v201 offset:1024
	ds_read_b128 v[180:183], v201 offset:2048
	ds_read_b128 v[184:187], v201 offset:3072
	ds_read_b128 v[188:191], v201 offset:4096
	ds_read_b128 v[192:195], v201 offset:5120
	ds_read_b128 v[202:205], v201 offset:6144
	ds_read_b128 v[206:209], v201 offset:7168
	global_load_lds_dwordx4 v[196:197], off
	v_lshl_add_u64 v[196:197], s[4:5], 0, v[178:179]
	s_add_i32 m0, s30, 0xe000
	s_nop 0
	global_load_lds_dwordx4 v[196:197], off
	s_waitcnt vmcnt(8)
	s_waitcnt lgkmcnt(0)
	s_barrier
	s_setprio 1
	s_waitcnt lgkmcnt(0)
	v_mfma_f32_16x16x32_bf16 v[146:149], v[58:61], v[162:165], 0
	v_mfma_f32_16x16x32_bf16 v[142:145], v[66:69], v[162:165], 0
	v_mfma_f32_16x16x32_bf16 v[126:129], v[58:61], v[180:183], 0
	v_mfma_f32_16x16x32_bf16 v[122:125], v[66:69], v[180:183], 0
	v_mfma_f32_16x16x32_bf16 v[110:113], v[58:61], v[188:191], 0
	v_mfma_f32_16x16x32_bf16 v[106:109], v[66:69], v[188:191], 0
	v_mfma_f32_16x16x32_bf16 v[94:97], v[58:61], v[202:205], 0
	v_mfma_f32_16x16x32_bf16 v[90:93], v[66:69], v[202:205], 0
	v_mfma_f32_16x16x32_bf16 v[146:149], v[62:65], v[166:169], v[146:149]
	v_mfma_f32_16x16x32_bf16 v[142:145], v[70:73], v[166:169], v[142:145]
	v_mfma_f32_16x16x32_bf16 v[126:129], v[62:65], v[184:187], v[126:129]
	v_mfma_f32_16x16x32_bf16 v[122:125], v[70:73], v[184:187], v[122:125]
	v_mfma_f32_16x16x32_bf16 v[110:113], v[62:65], v[192:195], v[110:113]
	v_mfma_f32_16x16x32_bf16 v[106:109], v[70:73], v[192:195], v[106:109]
	v_mfma_f32_16x16x32_bf16 v[94:97], v[62:65], v[206:209], v[94:97]
	v_mfma_f32_16x16x32_bf16 v[90:93], v[70:73], v[206:209], v[90:93]
	s_setprio 0
	s_setprio 1
	v_mfma_f32_16x16x32_bf16 v[134:137], v[138:141], v[162:165], 0
	v_mfma_f32_16x16x32_bf16 v[130:133], v[154:157], v[162:165], 0
	v_mfma_f32_16x16x32_bf16 v[118:121], v[138:141], v[180:183], 0
	v_mfma_f32_16x16x32_bf16 v[114:117], v[154:157], v[180:183], 0
	v_mfma_f32_16x16x32_bf16 v[102:105], v[138:141], v[188:191], 0
	v_mfma_f32_16x16x32_bf16 v[98:101], v[154:157], v[188:191], 0
	v_mfma_f32_16x16x32_bf16 v[86:89], v[138:141], v[202:205], 0
	v_mfma_f32_16x16x32_bf16 v[82:85], v[154:157], v[202:205], 0
	v_mfma_f32_16x16x32_bf16 v[134:137], v[150:153], v[166:169], v[134:137]
	v_mfma_f32_16x16x32_bf16 v[130:133], v[158:161], v[166:169], v[130:133]
	v_mfma_f32_16x16x32_bf16 v[118:121], v[150:153], v[184:187], v[118:121]
	v_mfma_f32_16x16x32_bf16 v[114:117], v[158:161], v[184:187], v[114:117]
	v_mfma_f32_16x16x32_bf16 v[102:105], v[150:153], v[192:195], v[102:105]
	v_mfma_f32_16x16x32_bf16 v[98:101], v[158:161], v[192:195], v[98:101]
	v_mfma_f32_16x16x32_bf16 v[86:89], v[150:153], v[206:209], v[86:89]
	v_mfma_f32_16x16x32_bf16 v[82:85], v[158:161], v[206:209], v[82:85]
	s_setprio 0
	s_barrier
	s_add_i32 s48, s48, s29
	v_lshl_add_u64 v[196:197], s[46:47], 0, v[0:1]
	s_mov_b32 m0, s48
	ds_read_b128 v[162:165], v201 offset:16384
	ds_read_b128 v[166:169], v201 offset:17408
	ds_read_b128 v[180:183], v201 offset:18432
	ds_read_b128 v[184:187], v201 offset:19456
	ds_read_b128 v[188:191], v201 offset:20480
	ds_read_b128 v[192:195], v201 offset:21504
	ds_read_b128 v[202:205], v201 offset:22528
	ds_read_b128 v[206:209], v201 offset:23552
	global_load_lds_dwordx4 v[196:197], off
	s_add_i32 m0, s48, 0x2000
	v_lshl_add_u64 v[210:211], s[46:47], 0, v[170:171]
	s_add_u32 s46, s46, s12
	s_addc_u32 s47, s47, 0
	s_add_i32 s45, s45, s29
	global_load_lds_dwordx4 v[210:211], off
	v_lshl_add_u64 v[212:213], s[46:47], 0, v[0:1]
	s_mov_b32 m0, s45
	v_lshl_add_u64 v[214:215], s[46:47], 0, v[170:171]
	global_load_lds_dwordx4 v[212:213], off
	s_add_i32 m0, s45, 0x2000
	v_lshl_add_u64 v[216:217], s[2:3], 0, v[174:175]
	global_load_lds_dwordx4 v[214:215], off
	s_mov_b32 m0, s30
	v_lshl_add_u64 v[218:219], s[2:3], 0, v[172:173]
	global_load_lds_dwordx4 v[216:217], off
	s_mov_b32 m0, s31
	s_nop 0
	global_load_lds_dwordx4 v[218:219], off
	s_waitcnt vmcnt(8)
	s_waitcnt lgkmcnt(0)
	s_barrier
	s_setprio 1
	s_waitcnt lgkmcnt(0)
	v_mfma_f32_16x16x32_bf16 v[78:81], v[58:61], v[162:165], 0
	v_mfma_f32_16x16x32_bf16 v[74:77], v[66:69], v[162:165], 0
	v_mfma_f32_16x16x32_bf16 v[46:49], v[58:61], v[180:183], 0
	v_mfma_f32_16x16x32_bf16 v[42:45], v[66:69], v[180:183], 0
	v_mfma_f32_16x16x32_bf16 v[30:33], v[58:61], v[188:191], 0
	v_mfma_f32_16x16x32_bf16 v[26:29], v[66:69], v[188:191], 0
	v_mfma_f32_16x16x32_bf16 v[14:17], v[58:61], v[202:205], 0
	v_mfma_f32_16x16x32_bf16 v[10:13], v[66:69], v[202:205], 0
	v_mfma_f32_16x16x32_bf16 v[78:81], v[62:65], v[166:169], v[78:81]
	v_mfma_f32_16x16x32_bf16 v[74:77], v[70:73], v[166:169], v[74:77]
	v_mfma_f32_16x16x32_bf16 v[46:49], v[62:65], v[184:187], v[46:49]
	v_mfma_f32_16x16x32_bf16 v[42:45], v[70:73], v[184:187], v[42:45]
	v_mfma_f32_16x16x32_bf16 v[30:33], v[62:65], v[192:195], v[30:33]
	v_mfma_f32_16x16x32_bf16 v[26:29], v[70:73], v[192:195], v[26:29]
	v_mfma_f32_16x16x32_bf16 v[14:17], v[62:65], v[206:209], v[14:17]
	v_mfma_f32_16x16x32_bf16 v[10:13], v[70:73], v[206:209], v[10:13]
	s_setprio 0
	s_setprio 1
	v_mfma_f32_16x16x32_bf16 v[54:57], v[138:141], v[162:165], 0
	v_mfma_f32_16x16x32_bf16 v[50:53], v[154:157], v[162:165], 0
	v_mfma_f32_16x16x32_bf16 v[38:41], v[138:141], v[180:183], 0
	v_mfma_f32_16x16x32_bf16 v[34:37], v[154:157], v[180:183], 0
	v_mfma_f32_16x16x32_bf16 v[22:25], v[138:141], v[188:191], 0
	v_mfma_f32_16x16x32_bf16 v[18:21], v[154:157], v[188:191], 0
	v_mfma_f32_16x16x32_bf16 v[6:9], v[138:141], v[202:205], 0
	v_mfma_f32_16x16x32_bf16 v[2:5], v[154:157], v[202:205], 0
	v_mfma_f32_16x16x32_bf16 v[54:57], v[150:153], v[166:169], v[54:57]
	v_mfma_f32_16x16x32_bf16 v[50:53], v[158:161], v[166:169], v[50:53]
	v_mfma_f32_16x16x32_bf16 v[38:41], v[150:153], v[184:187], v[38:41]
	v_mfma_f32_16x16x32_bf16 v[34:37], v[158:161], v[184:187], v[34:37]
	v_mfma_f32_16x16x32_bf16 v[22:25], v[150:153], v[192:195], v[22:25]
	v_mfma_f32_16x16x32_bf16 v[18:21], v[158:161], v[192:195], v[18:21]
	v_mfma_f32_16x16x32_bf16 v[6:9], v[150:153], v[206:209], v[6:9]
	v_mfma_f32_16x16x32_bf16 v[2:5], v[158:161], v[206:209], v[2:5]
	s_setprio 0
	s_barrier
	s_add_i32 s45, 0, 0x18000
	s_add_i32 s46, 0, 0x1c000
	v_add_u32_e32 v70, s45, v199
	v_add_u32_e32 v158, s46, v199
	ds_read_b128 v[58:61], v70
	ds_read_b128 v[62:65], v70 offset:1024
	ds_read_b128 v[66:69], v70 offset:2048
	ds_read_b128 v[70:73], v70 offset:3072
	ds_read_b128 v[138:141], v158
	ds_read_b128 v[150:153], v158 offset:1024
	ds_read_b128 v[154:157], v158 offset:2048
	ds_read_b128 v[158:161], v158 offset:3072
	s_add_u32 s2, s2, s12
	s_addc_u32 s3, s3, 0
	s_mov_b32 m0, s34
	v_lshl_add_u64 v[220:221], s[2:3], 0, v[174:175]
	ds_read_b128 v[162:165], v201 offset:32768
	ds_read_b128 v[166:169], v201 offset:33792
	ds_read_b128 v[180:183], v201 offset:34816
	ds_read_b128 v[184:187], v201 offset:35840
	ds_read_b128 v[188:191], v201 offset:36864
	ds_read_b128 v[192:195], v201 offset:37888
	ds_read_b128 v[202:205], v201 offset:38912
	ds_read_b128 v[206:209], v201 offset:39936
	global_load_lds_dwordx4 v[220:221], off
	v_lshl_add_u64 v[220:221], s[2:3], 0, v[172:173]
	s_mov_b32 m0, s35
	s_nop 0
	global_load_lds_dwordx4 v[220:221], off
	s_waitcnt vmcnt(8)
	s_waitcnt lgkmcnt(0)
	s_barrier
	s_setprio 1
	s_waitcnt lgkmcnt(0)
	v_mfma_f32_16x16x32_bf16 v[146:149], v[58:61], v[162:165], v[146:149]
	v_mfma_f32_16x16x32_bf16 v[142:145], v[66:69], v[162:165], v[142:145]
	v_mfma_f32_16x16x32_bf16 v[126:129], v[58:61], v[180:183], v[126:129]
	v_mfma_f32_16x16x32_bf16 v[122:125], v[66:69], v[180:183], v[122:125]
	v_mfma_f32_16x16x32_bf16 v[110:113], v[58:61], v[188:191], v[110:113]
	v_mfma_f32_16x16x32_bf16 v[106:109], v[66:69], v[188:191], v[106:109]
	v_mfma_f32_16x16x32_bf16 v[94:97], v[58:61], v[202:205], v[94:97]
	v_mfma_f32_16x16x32_bf16 v[90:93], v[66:69], v[202:205], v[90:93]
	v_mfma_f32_16x16x32_bf16 v[146:149], v[62:65], v[166:169], v[146:149]
	v_mfma_f32_16x16x32_bf16 v[142:145], v[70:73], v[166:169], v[142:145]
	v_mfma_f32_16x16x32_bf16 v[126:129], v[62:65], v[184:187], v[126:129]
	v_mfma_f32_16x16x32_bf16 v[122:125], v[70:73], v[184:187], v[122:125]
	v_mfma_f32_16x16x32_bf16 v[110:113], v[62:65], v[192:195], v[110:113]
	v_mfma_f32_16x16x32_bf16 v[106:109], v[70:73], v[192:195], v[106:109]
	v_mfma_f32_16x16x32_bf16 v[94:97], v[62:65], v[206:209], v[94:97]
	v_mfma_f32_16x16x32_bf16 v[90:93], v[70:73], v[206:209], v[90:93]
	s_setprio 0
	s_setprio 1
	v_mfma_f32_16x16x32_bf16 v[134:137], v[138:141], v[162:165], v[134:137]
	v_mfma_f32_16x16x32_bf16 v[130:133], v[154:157], v[162:165], v[130:133]
	v_mfma_f32_16x16x32_bf16 v[118:121], v[138:141], v[180:183], v[118:121]
	v_mfma_f32_16x16x32_bf16 v[114:117], v[154:157], v[180:183], v[114:117]
	v_mfma_f32_16x16x32_bf16 v[102:105], v[138:141], v[188:191], v[102:105]
	v_mfma_f32_16x16x32_bf16 v[98:101], v[154:157], v[188:191], v[98:101]
	v_mfma_f32_16x16x32_bf16 v[86:89], v[138:141], v[202:205], v[86:89]
	v_mfma_f32_16x16x32_bf16 v[82:85], v[154:157], v[202:205], v[82:85]
	v_mfma_f32_16x16x32_bf16 v[134:137], v[150:153], v[166:169], v[134:137]
	v_mfma_f32_16x16x32_bf16 v[130:133], v[158:161], v[166:169], v[130:133]
	v_mfma_f32_16x16x32_bf16 v[118:121], v[150:153], v[184:187], v[118:121]
	v_mfma_f32_16x16x32_bf16 v[114:117], v[158:161], v[184:187], v[114:117]
	v_mfma_f32_16x16x32_bf16 v[102:105], v[150:153], v[192:195], v[102:105]
	v_mfma_f32_16x16x32_bf16 v[98:101], v[158:161], v[192:195], v[98:101]
	v_mfma_f32_16x16x32_bf16 v[86:89], v[150:153], v[206:209], v[86:89]
	v_mfma_f32_16x16x32_bf16 v[82:85], v[158:161], v[206:209], v[82:85]
	s_setprio 0
	s_barrier
	s_add_i32 s2, s45, s29
	v_lshl_add_u64 v[196:197], v[196:197], 0, s[74:75]
	s_mov_b32 m0, s2
	ds_read_b128 v[162:165], v201 offset:49152
	ds_read_b128 v[166:169], v201 offset:50176
	ds_read_b128 v[180:183], v201 offset:51200
	ds_read_b128 v[184:187], v201 offset:52224
	ds_read_b128 v[188:191], v201 offset:53248
	ds_read_b128 v[192:195], v201 offset:54272
	ds_read_b128 v[202:205], v201 offset:55296
	ds_read_b128 v[206:209], v201 offset:56320
	global_load_lds_dwordx4 v[196:197], off
	v_lshl_add_u64 v[196:197], v[210:211], 0, s[74:75]
	s_add_i32 m0, s2, 0x2000
	s_add_i32 s2, s46, s29
	global_load_lds_dwordx4 v[196:197], off
	v_lshl_add_u64 v[196:197], v[212:213], 0, s[74:75]
	s_mov_b32 m0, s2
	s_nop 0
	global_load_lds_dwordx4 v[196:197], off
	v_lshl_add_u64 v[196:197], v[214:215], 0, s[74:75]
	s_add_i32 m0, s2, 0x2000
	s_nop 0
	global_load_lds_dwordx4 v[196:197], off
	v_lshl_add_u64 v[196:197], v[216:217], 0, s[74:75]
	s_mov_b32 m0, s38
	s_nop 0
	global_load_lds_dwordx4 v[196:197], off
	v_lshl_add_u64 v[196:197], v[218:219], 0, s[74:75]
	s_mov_b32 m0, s39
	s_nop 0
	global_load_lds_dwordx4 v[196:197], off
	s_waitcnt vmcnt(8)
	s_waitcnt lgkmcnt(0)
	s_barrier
	s_setprio 1
	s_waitcnt lgkmcnt(0)
	v_mfma_f32_16x16x32_bf16 v[78:81], v[58:61], v[162:165], v[78:81]
	v_mfma_f32_16x16x32_bf16 v[74:77], v[66:69], v[162:165], v[74:77]
	v_mfma_f32_16x16x32_bf16 v[46:49], v[58:61], v[180:183], v[46:49]
	v_mfma_f32_16x16x32_bf16 v[42:45], v[66:69], v[180:183], v[42:45]
	v_mfma_f32_16x16x32_bf16 v[30:33], v[58:61], v[188:191], v[30:33]
	v_mfma_f32_16x16x32_bf16 v[26:29], v[66:69], v[188:191], v[26:29]
	v_mfma_f32_16x16x32_bf16 v[14:17], v[58:61], v[202:205], v[14:17]
	v_mfma_f32_16x16x32_bf16 v[10:13], v[66:69], v[202:205], v[10:13]
	v_mfma_f32_16x16x32_bf16 v[78:81], v[62:65], v[166:169], v[78:81]
	v_mfma_f32_16x16x32_bf16 v[74:77], v[70:73], v[166:169], v[74:77]
	v_mfma_f32_16x16x32_bf16 v[46:49], v[62:65], v[184:187], v[46:49]
	v_mfma_f32_16x16x32_bf16 v[42:45], v[70:73], v[184:187], v[42:45]
	v_mfma_f32_16x16x32_bf16 v[30:33], v[62:65], v[192:195], v[30:33]
	v_mfma_f32_16x16x32_bf16 v[26:29], v[70:73], v[192:195], v[26:29]
	v_mfma_f32_16x16x32_bf16 v[14:17], v[62:65], v[206:209], v[14:17]
	v_mfma_f32_16x16x32_bf16 v[10:13], v[70:73], v[206:209], v[10:13]
	s_setprio 0
	s_setprio 1
	v_mfma_f32_16x16x32_bf16 v[54:57], v[138:141], v[162:165], v[54:57]
	v_mfma_f32_16x16x32_bf16 v[50:53], v[154:157], v[162:165], v[50:53]
	v_mfma_f32_16x16x32_bf16 v[38:41], v[138:141], v[180:183], v[38:41]
	v_mfma_f32_16x16x32_bf16 v[34:37], v[154:157], v[180:183], v[34:37]
	v_mfma_f32_16x16x32_bf16 v[22:25], v[138:141], v[188:191], v[22:25]
	v_mfma_f32_16x16x32_bf16 v[18:21], v[154:157], v[188:191], v[18:21]
	v_mfma_f32_16x16x32_bf16 v[6:9], v[138:141], v[202:205], v[6:9]
	v_mfma_f32_16x16x32_bf16 v[2:5], v[154:157], v[202:205], v[2:5]
	v_mfma_f32_16x16x32_bf16 v[54:57], v[150:153], v[166:169], v[54:57]
	v_mfma_f32_16x16x32_bf16 v[50:53], v[158:161], v[166:169], v[50:53]
	v_mfma_f32_16x16x32_bf16 v[38:41], v[150:153], v[184:187], v[38:41]
	v_mfma_f32_16x16x32_bf16 v[34:37], v[158:161], v[184:187], v[34:37]
	v_mfma_f32_16x16x32_bf16 v[22:25], v[150:153], v[192:195], v[22:25]
	v_mfma_f32_16x16x32_bf16 v[18:21], v[158:161], v[192:195], v[18:21]
	v_mfma_f32_16x16x32_bf16 v[6:9], v[150:153], v[206:209], v[6:9]
	v_mfma_f32_16x16x32_bf16 v[2:5], v[158:161], v[206:209], v[2:5]
	s_setprio 0
	s_barrier
	s_add_u32 s4, s4, 0x100
	s_addc_u32 s5, s5, 0
	s_add_u32 s26, s26, 0x100
	s_addc_u32 s27, s27, 0
	s_cmp_ge_u32 s33, s37
	s_mov_b32 s2, s33

.LBB0_597:
	s_ashr_i32 s9, s8, 31
	s_lshl_b64 s[12:13], s[8:9], 19
	s_add_u32 s12, s82, s12
	s_addc_u32 s13, s83, s13
	s_and_b64 s[14:15], s[0:1], exec
	s_cselect_b32 s9, s13, s17
	s_cselect_b32 s34, s12, s16
	s_ashr_i32 s11, s10, 31
	s_lshl_b64 s[14:15], s[10:11], 19
	s_add_u32 s14, s20, s14
	s_addc_u32 s15, s21, s15
	s_and_b64 s[18:19], s[0:1], exec
	s_cselect_b32 s11, s15, s3
	s_cselect_b32 s35, s14, s2
	s_add_u32 s16, s16, 0x40080
	s_addc_u32 s17, s17, 0
	s_add_u32 s33, s2, 0x100
	s_addc_u32 s36, s3, 0
	s_mov_b32 s37, -2
	s_add_u32 s2, s16, 0xfffc0080
	s_addc_u32 s3, s17, -1
	s_add_i32 s38, 0, 0x10000
	s_cmp_eq_u32 s37, 12
	s_cselect_b32 s19, s9, s3
	s_cselect_b32 s18, s34, s2
	s_cselect_b32 s3, s11, s36
	s_cselect_b32 s2, s35, s33
	s_add_i32 s40, 0, 0x14000
	v_add_u32_e32 v154, s38, v159
	v_add_u32_e32 v174, s40, v159
	ds_read_b128 v[142:145], v154
	ds_read_b128 v[146:149], v154 offset:1024
	ds_read_b128 v[150:153], v154 offset:2048
	ds_read_b128 v[154:157], v154 offset:3072
	ds_read_b128 v[162:165], v174
	ds_read_b128 v[166:169], v174 offset:1024
	ds_read_b128 v[170:173], v174 offset:2048
	ds_read_b128 v[174:177], v174 offset:3072
	v_lshl_add_u64 v[210:211], s[16:17], 0, v[138:139]
	s_add_i32 m0, s23, 0xc000
	ds_read_b128 v[178:181], v161
	ds_read_b128 v[182:185], v161 offset:1024
	ds_read_b128 v[186:189], v161 offset:2048
	ds_read_b128 v[190:193], v161 offset:3072
	ds_read_b128 v[194:197], v161 offset:4096
	ds_read_b128 v[198:201], v161 offset:5120
	ds_read_b128 v[202:205], v161 offset:6144
	ds_read_b128 v[206:209], v161 offset:7168
	global_load_lds_dwordx4 v[210:211], off
	v_lshl_add_u64 v[210:211], s[16:17], 0, v[140:141]
	s_add_i32 m0, s23, 0xe000
	s_nop 0
	global_load_lds_dwordx4 v[210:211], off
	s_waitcnt vmcnt(8)
	s_waitcnt lgkmcnt(0)
	s_barrier
	s_setprio 1
	s_waitcnt lgkmcnt(0)
	v_mfma_f32_16x16x32_bf16 v[126:129], v[142:145], v[178:181], 0
	v_mfma_f32_16x16x32_bf16 v[118:121], v[150:153], v[178:181], 0
	v_mfma_f32_16x16x32_bf16 v[110:113], v[142:145], v[186:189], 0
	v_mfma_f32_16x16x32_bf16 v[102:105], v[150:153], v[186:189], 0
	v_mfma_f32_16x16x32_bf16 v[94:97], v[142:145], v[194:197], 0
	v_mfma_f32_16x16x32_bf16 v[86:89], v[150:153], v[194:197], 0
	v_mfma_f32_16x16x32_bf16 v[78:81], v[142:145], v[202:205], 0
	v_mfma_f32_16x16x32_bf16 v[70:73], v[150:153], v[202:205], 0
	v_mfma_f32_16x16x32_bf16 v[126:129], v[146:149], v[182:185], v[126:129]
	v_mfma_f32_16x16x32_bf16 v[118:121], v[154:157], v[182:185], v[118:121]
	v_mfma_f32_16x16x32_bf16 v[110:113], v[146:149], v[190:193], v[110:113]
	v_mfma_f32_16x16x32_bf16 v[102:105], v[154:157], v[190:193], v[102:105]
	v_mfma_f32_16x16x32_bf16 v[94:97], v[146:149], v[198:201], v[94:97]
	v_mfma_f32_16x16x32_bf16 v[86:89], v[154:157], v[198:201], v[86:89]
	v_mfma_f32_16x16x32_bf16 v[78:81], v[146:149], v[206:209], v[78:81]
	v_mfma_f32_16x16x32_bf16 v[70:73], v[154:157], v[206:209], v[70:73]
	s_setprio 0
	s_setprio 1
	v_mfma_f32_16x16x32_bf16 v[122:125], v[162:165], v[178:181], 0
	v_mfma_f32_16x16x32_bf16 v[114:117], v[170:173], v[178:181], 0
	v_mfma_f32_16x16x32_bf16 v[106:109], v[162:165], v[186:189], 0
	v_mfma_f32_16x16x32_bf16 v[98:101], v[170:173], v[186:189], 0
	v_mfma_f32_16x16x32_bf16 v[90:93], v[162:165], v[194:197], 0
	v_mfma_f32_16x16x32_bf16 v[82:85], v[170:173], v[194:197], 0
	v_mfma_f32_16x16x32_bf16 v[74:77], v[162:165], v[202:205], 0
	v_mfma_f32_16x16x32_bf16 v[66:69], v[170:173], v[202:205], 0
	v_mfma_f32_16x16x32_bf16 v[122:125], v[166:169], v[182:185], v[122:125]
	v_mfma_f32_16x16x32_bf16 v[114:117], v[174:177], v[182:185], v[114:117]
	v_mfma_f32_16x16x32_bf16 v[106:109], v[166:169], v[190:193], v[106:109]
	v_mfma_f32_16x16x32_bf16 v[98:101], v[174:177], v[190:193], v[98:101]
	v_mfma_f32_16x16x32_bf16 v[90:93], v[166:169], v[198:201], v[90:93]
	v_mfma_f32_16x16x32_bf16 v[82:85], v[174:177], v[198:201], v[82:85]
	v_mfma_f32_16x16x32_bf16 v[74:77], v[166:169], v[206:209], v[74:77]
	v_mfma_f32_16x16x32_bf16 v[66:69], v[174:177], v[206:209], v[66:69]
	s_setprio 0
	s_barrier
	s_add_i32 s38, s38, s22
	v_lshl_add_u64 v[210:211], s[2:3], 0, v[0:1]
	s_mov_b32 m0, s38
	ds_read_b128 v[178:181], v161 offset:16384
	ds_read_b128 v[182:185], v161 offset:17408
	ds_read_b128 v[186:189], v161 offset:18432
	ds_read_b128 v[190:193], v161 offset:19456
	ds_read_b128 v[194:197], v161 offset:20480
	ds_read_b128 v[198:201], v161 offset:21504
	ds_read_b128 v[202:205], v161 offset:22528
	ds_read_b128 v[206:209], v161 offset:23552
	global_load_lds_dwordx4 v[210:211], off
	s_add_i32 m0, s38, 0x2000
	s_add_u32 s38, s2, 0x40000
	v_lshl_add_u64 v[212:213], s[2:3], 0, v[130:131]
	s_addc_u32 s39, s3, 0
	s_add_i32 s40, s40, s22
	global_load_lds_dwordx4 v[212:213], off
	v_lshl_add_u64 v[214:215], s[38:39], 0, v[0:1]
	s_mov_b32 m0, s40
	v_lshl_add_u64 v[216:217], s[18:19], 0, v[132:133]
	global_load_lds_dwordx4 v[214:215], off
	v_lshl_add_u64 v[214:215], s[38:39], 0, v[130:131]
	s_add_i32 m0, s40, 0x2000
	s_nop 0
	global_load_lds_dwordx4 v[214:215], off
	v_lshl_add_u64 v[214:215], s[18:19], 0, v[134:135]
	s_mov_b32 m0, s23
	s_nop 0
	global_load_lds_dwordx4 v[214:215], off
	s_mov_b32 m0, s24
	s_nop 0
	global_load_lds_dwordx4 v[216:217], off
	s_waitcnt vmcnt(8)
	s_waitcnt lgkmcnt(0)
	s_barrier
	s_setprio 1
	s_waitcnt lgkmcnt(0)
	v_mfma_f32_16x16x32_bf16 v[62:65], v[142:145], v[178:181], 0
	v_mfma_f32_16x16x32_bf16 v[54:57], v[150:153], v[178:181], 0
	v_mfma_f32_16x16x32_bf16 v[46:49], v[142:145], v[186:189], 0
	v_mfma_f32_16x16x32_bf16 v[38:41], v[150:153], v[186:189], 0
	v_mfma_f32_16x16x32_bf16 v[30:33], v[142:145], v[194:197], 0
	v_mfma_f32_16x16x32_bf16 v[22:25], v[150:153], v[194:197], 0
	v_mfma_f32_16x16x32_bf16 v[14:17], v[142:145], v[202:205], 0
	v_mfma_f32_16x16x32_bf16 v[6:9], v[150:153], v[202:205], 0
	v_mfma_f32_16x16x32_bf16 v[62:65], v[146:149], v[182:185], v[62:65]
	v_mfma_f32_16x16x32_bf16 v[54:57], v[154:157], v[182:185], v[54:57]
	v_mfma_f32_16x16x32_bf16 v[46:49], v[146:149], v[190:193], v[46:49]
	v_mfma_f32_16x16x32_bf16 v[38:41], v[154:157], v[190:193], v[38:41]
	v_mfma_f32_16x16x32_bf16 v[30:33], v[146:149], v[198:201], v[30:33]
	v_mfma_f32_16x16x32_bf16 v[22:25], v[154:157], v[198:201], v[22:25]
	v_mfma_f32_16x16x32_bf16 v[14:17], v[146:149], v[206:209], v[14:17]
	v_mfma_f32_16x16x32_bf16 v[6:9], v[154:157], v[206:209], v[6:9]
	s_setprio 0
	s_setprio 1
	v_mfma_f32_16x16x32_bf16 v[58:61], v[162:165], v[178:181], 0
	v_mfma_f32_16x16x32_bf16 v[50:53], v[170:173], v[178:181], 0
	v_mfma_f32_16x16x32_bf16 v[42:45], v[162:165], v[186:189], 0
	v_mfma_f32_16x16x32_bf16 v[34:37], v[170:173], v[186:189], 0
	v_mfma_f32_16x16x32_bf16 v[26:29], v[162:165], v[194:197], 0
	v_mfma_f32_16x16x32_bf16 v[18:21], v[170:173], v[194:197], 0
	v_mfma_f32_16x16x32_bf16 v[10:13], v[162:165], v[202:205], 0
	v_mfma_f32_16x16x32_bf16 v[2:5], v[170:173], v[202:205], 0
	v_mfma_f32_16x16x32_bf16 v[58:61], v[166:169], v[182:185], v[58:61]
	v_mfma_f32_16x16x32_bf16 v[50:53], v[174:177], v[182:185], v[50:53]
	v_mfma_f32_16x16x32_bf16 v[42:45], v[166:169], v[190:193], v[42:45]
	v_mfma_f32_16x16x32_bf16 v[34:37], v[174:177], v[190:193], v[34:37]
	v_mfma_f32_16x16x32_bf16 v[26:29], v[166:169], v[198:201], v[26:29]
	v_mfma_f32_16x16x32_bf16 v[18:21], v[174:177], v[198:201], v[18:21]
	v_mfma_f32_16x16x32_bf16 v[10:13], v[166:169], v[206:209], v[10:13]
	v_mfma_f32_16x16x32_bf16 v[2:5], v[174:177], v[206:209], v[2:5]
	s_setprio 0
	s_barrier
	s_add_i32 s38, 0, 0x18000
	s_add_i32 s39, 0, 0x1c000
	v_add_u32_e32 v154, s38, v159
	v_add_u32_e32 v174, s39, v159
	ds_read_b128 v[142:145], v154
	ds_read_b128 v[146:149], v154 offset:1024
	ds_read_b128 v[150:153], v154 offset:2048
	ds_read_b128 v[154:157], v154 offset:3072
	ds_read_b128 v[162:165], v174
	ds_read_b128 v[166:169], v174 offset:1024
	ds_read_b128 v[170:173], v174 offset:2048
	ds_read_b128 v[174:177], v174 offset:3072
	s_add_u32 s18, s18, 0x40000
	s_addc_u32 s19, s19, 0
	s_mov_b32 m0, s25
	v_lshl_add_u64 v[218:219], s[18:19], 0, v[134:135]
	ds_read_b128 v[178:181], v161 offset:32768
	ds_read_b128 v[182:185], v161 offset:33792
	ds_read_b128 v[186:189], v161 offset:34816
	ds_read_b128 v[190:193], v161 offset:35840
	ds_read_b128 v[194:197], v161 offset:36864
	ds_read_b128 v[198:201], v161 offset:37888
	ds_read_b128 v[202:205], v161 offset:38912
	ds_read_b128 v[206:209], v161 offset:39936
	global_load_lds_dwordx4 v[218:219], off
	v_lshl_add_u64 v[218:219], s[18:19], 0, v[132:133]
	s_mov_b32 m0, s26
	s_nop 0
	global_load_lds_dwordx4 v[218:219], off
	s_waitcnt vmcnt(8)
	s_waitcnt lgkmcnt(0)
	s_barrier
	s_setprio 1
	s_waitcnt lgkmcnt(0)
	v_mfma_f32_16x16x32_bf16 v[126:129], v[142:145], v[178:181], v[126:129]
	v_mfma_f32_16x16x32_bf16 v[118:121], v[150:153], v[178:181], v[118:121]
	v_mfma_f32_16x16x32_bf16 v[110:113], v[142:145], v[186:189], v[110:113]
	v_mfma_f32_16x16x32_bf16 v[102:105], v[150:153], v[186:189], v[102:105]
	v_mfma_f32_16x16x32_bf16 v[94:97], v[142:145], v[194:197], v[94:97]
	v_mfma_f32_16x16x32_bf16 v[86:89], v[150:153], v[194:197], v[86:89]
	v_mfma_f32_16x16x32_bf16 v[78:81], v[142:145], v[202:205], v[78:81]
	v_mfma_f32_16x16x32_bf16 v[70:73], v[150:153], v[202:205], v[70:73]
	v_mfma_f32_16x16x32_bf16 v[126:129], v[146:149], v[182:185], v[126:129]
	v_mfma_f32_16x16x32_bf16 v[118:121], v[154:157], v[182:185], v[118:121]
	v_mfma_f32_16x16x32_bf16 v[110:113], v[146:149], v[190:193], v[110:113]
	v_mfma_f32_16x16x32_bf16 v[102:105], v[154:157], v[190:193], v[102:105]
	v_mfma_f32_16x16x32_bf16 v[94:97], v[146:149], v[198:201], v[94:97]
	v_mfma_f32_16x16x32_bf16 v[86:89], v[154:157], v[198:201], v[86:89]
	v_mfma_f32_16x16x32_bf16 v[78:81], v[146:149], v[206:209], v[78:81]
	v_mfma_f32_16x16x32_bf16 v[70:73], v[154:157], v[206:209], v[70:73]
	s_setprio 0
	s_setprio 1
	v_mfma_f32_16x16x32_bf16 v[122:125], v[162:165], v[178:181], v[122:125]
	v_mfma_f32_16x16x32_bf16 v[114:117], v[170:173], v[178:181], v[114:117]
	v_mfma_f32_16x16x32_bf16 v[106:109], v[162:165], v[186:189], v[106:109]
	v_mfma_f32_16x16x32_bf16 v[98:101], v[170:173], v[186:189], v[98:101]
	v_mfma_f32_16x16x32_bf16 v[90:93], v[162:165], v[194:197], v[90:93]
	v_mfma_f32_16x16x32_bf16 v[82:85], v[170:173], v[194:197], v[82:85]
	v_mfma_f32_16x16x32_bf16 v[74:77], v[162:165], v[202:205], v[74:77]
	v_mfma_f32_16x16x32_bf16 v[66:69], v[170:173], v[202:205], v[66:69]
	v_mfma_f32_16x16x32_bf16 v[122:125], v[166:169], v[182:185], v[122:125]
	v_mfma_f32_16x16x32_bf16 v[114:117], v[174:177], v[182:185], v[114:117]
	v_mfma_f32_16x16x32_bf16 v[106:109], v[166:169], v[190:193], v[106:109]
	v_mfma_f32_16x16x32_bf16 v[98:101], v[174:177], v[190:193], v[98:101]
	v_mfma_f32_16x16x32_bf16 v[90:93], v[166:169], v[198:201], v[90:93]
	v_mfma_f32_16x16x32_bf16 v[82:85], v[174:177], v[198:201], v[82:85]
	v_mfma_f32_16x16x32_bf16 v[74:77], v[166:169], v[206:209], v[74:77]
	v_mfma_f32_16x16x32_bf16 v[66:69], v[174:177], v[206:209], v[66:69]
	s_setprio 0
	s_barrier
	s_add_i32 s18, s38, s22
	v_lshl_add_u64 v[210:211], v[210:211], 0, s[74:75]
	s_mov_b32 m0, s18
	ds_read_b128 v[178:181], v161 offset:49152
	ds_read_b128 v[182:185], v161 offset:50176
	ds_read_b128 v[186:189], v161 offset:51200
	ds_read_b128 v[190:193], v161 offset:52224
	ds_read_b128 v[194:197], v161 offset:53248
	ds_read_b128 v[198:201], v161 offset:54272
	ds_read_b128 v[202:205], v161 offset:55296
	ds_read_b128 v[206:209], v161 offset:56320
	global_load_lds_dwordx4 v[210:211], off
	s_add_i32 m0, s18, 0x2000
	s_add_u32 s2, s2, 0x40080
	v_lshl_add_u64 v[210:211], v[212:213], 0, s[74:75]
	s_addc_u32 s3, s3, 0
	s_add_i32 s18, s39, s22
	global_load_lds_dwordx4 v[210:211], off
	v_lshl_add_u64 v[210:211], s[2:3], 0, v[0:1]
	s_mov_b32 m0, s18
	s_nop 0
	global_load_lds_dwordx4 v[210:211], off
	v_lshl_add_u64 v[210:211], s[2:3], 0, v[130:131]
	s_add_i32 m0, s18, 0x2000
	s_nop 0
	global_load_lds_dwordx4 v[210:211], off
	v_lshl_add_u64 v[210:211], v[214:215], 0, s[74:75]
	s_mov_b32 m0, s27
	s_nop 0
	global_load_lds_dwordx4 v[210:211], off
	v_lshl_add_u64 v[210:211], v[216:217], 0, s[74:75]
	s_mov_b32 m0, s28
	s_nop 0
	global_load_lds_dwordx4 v[210:211], off
	s_waitcnt vmcnt(8)
	s_waitcnt lgkmcnt(0)
	s_barrier
	s_setprio 1
	s_waitcnt lgkmcnt(0)
	v_mfma_f32_16x16x32_bf16 v[62:65], v[142:145], v[178:181], v[62:65]
	v_mfma_f32_16x16x32_bf16 v[54:57], v[150:153], v[178:181], v[54:57]
	v_mfma_f32_16x16x32_bf16 v[46:49], v[142:145], v[186:189], v[46:49]
	v_mfma_f32_16x16x32_bf16 v[38:41], v[150:153], v[186:189], v[38:41]
	v_mfma_f32_16x16x32_bf16 v[30:33], v[142:145], v[194:197], v[30:33]
	v_mfma_f32_16x16x32_bf16 v[22:25], v[150:153], v[194:197], v[22:25]
	v_mfma_f32_16x16x32_bf16 v[14:17], v[142:145], v[202:205], v[14:17]
	v_mfma_f32_16x16x32_bf16 v[6:9], v[150:153], v[202:205], v[6:9]
	v_mfma_f32_16x16x32_bf16 v[62:65], v[146:149], v[182:185], v[62:65]
	v_mfma_f32_16x16x32_bf16 v[54:57], v[154:157], v[182:185], v[54:57]
	v_mfma_f32_16x16x32_bf16 v[46:49], v[146:149], v[190:193], v[46:49]
	v_mfma_f32_16x16x32_bf16 v[38:41], v[154:157], v[190:193], v[38:41]
	v_mfma_f32_16x16x32_bf16 v[30:33], v[146:149], v[198:201], v[30:33]
	v_mfma_f32_16x16x32_bf16 v[22:25], v[154:157], v[198:201], v[22:25]
	v_mfma_f32_16x16x32_bf16 v[14:17], v[146:149], v[206:209], v[14:17]
	v_mfma_f32_16x16x32_bf16 v[6:9], v[154:157], v[206:209], v[6:9]
	s_setprio 0
	s_setprio 1
	v_mfma_f32_16x16x32_bf16 v[58:61], v[162:165], v[178:181], v[58:61]
	v_mfma_f32_16x16x32_bf16 v[50:53], v[170:173], v[178:181], v[50:53]
	v_mfma_f32_16x16x32_bf16 v[42:45], v[162:165], v[186:189], v[42:45]
	v_mfma_f32_16x16x32_bf16 v[34:37], v[170:173], v[186:189], v[34:37]
	v_mfma_f32_16x16x32_bf16 v[26:29], v[162:165], v[194:197], v[26:29]
	v_mfma_f32_16x16x32_bf16 v[18:21], v[170:173], v[194:197], v[18:21]
	v_mfma_f32_16x16x32_bf16 v[10:13], v[162:165], v[202:205], v[10:13]
	v_mfma_f32_16x16x32_bf16 v[2:5], v[170:173], v[202:205], v[2:5]
	v_mfma_f32_16x16x32_bf16 v[58:61], v[166:169], v[182:185], v[58:61]
	v_mfma_f32_16x16x32_bf16 v[50:53], v[174:177], v[182:185], v[50:53]
	v_mfma_f32_16x16x32_bf16 v[42:45], v[166:169], v[190:193], v[42:45]
	v_mfma_f32_16x16x32_bf16 v[34:37], v[174:177], v[190:193], v[34:37]
	v_mfma_f32_16x16x32_bf16 v[26:29], v[166:169], v[198:201], v[26:29]
	v_mfma_f32_16x16x32_bf16 v[18:21], v[174:177], v[198:201], v[18:21]
	v_mfma_f32_16x16x32_bf16 v[10:13], v[166:169], v[206:209], v[10:13]
	v_mfma_f32_16x16x32_bf16 v[2:5], v[174:177], v[206:209], v[2:5]
	s_setprio 0
	s_barrier
	s_add_i32 s37, s37, 2
	s_add_u32 s16, s16, 0x100
	s_addc_u32 s17, s17, 0
	s_add_u32 s33, s33, 0x100
	s_addc_u32 s36, s36, 0
	s_cmp_gt_u32 s37, 13
